# top-16 threshold searches leave the bit descent once the accepted threshold isolates exactly 16 keys
# baseline (speedup 1.0000x reference)
.LBB0_1526:
	s_or_b64 exec, exec, s[0:1]
	s_waitcnt vmcnt(2)
	v_lshl_add_u32 v0, v157, 2, v158
	s_waitcnt lgkmcnt(0)
	ds_read2st64_b32 v[2:3], v0 offset0:128 offset1:129
	s_ashr_i32 s86, s50, 1
	s_add_i32 s22, s86, -1
	v_cmp_eq_u32_e32 vcc, 0, v157
	v_cmp_eq_u32_e64 s[0:1], s86, v157
	s_waitcnt lgkmcnt(0)
	v_max_f32_e32 v1, v2, v2
	s_or_b64 s[0:1], vcc, s[0:1]
	v_cmp_eq_u32_e32 vcc, s22, v157
	s_waitcnt vmcnt(1)
	ds_read2st64_b32 v[4:5], v0 offset0:130 offset1:131
	v_max_f32_e32 v1, 0, v1
	v_and_b32_e32 v1, 0xfffffe00, v1
	s_or_b64 s[10:11], s[0:1], vcc
	v_cndmask_b32_e64 v1, v1, v172, s[10:11]
	v_lshlrev_b32_e32 v6, 1, v157
	v_bitop3_b32 v1, v1, v6, s4 bitop3:0xf6
	v_cmp_lt_i32_e64 s[12:13], s86, v157
	v_xor_b32_e32 v2, 0x1ff, v6
	v_max_f32_e32 v3, v3, v3
	v_cndmask_b32_e64 v6, v1, 0, s[12:13]
	v_or_b32_e32 v1, 64, v157
	v_cmp_eq_u32_e32 vcc, s86, v1
	v_cmp_eq_u32_e64 s[0:1], s22, v1
	v_max_f32_e32 v3, 0, v3
	v_lshlrev_b32_e32 v8, 1, v1
	v_cmp_lt_i32_e64 s[16:17], s86, v1
	v_or_b32_e32 v1, 0x80, v157
	s_waitcnt lgkmcnt(0)
	v_max_f32_e32 v4, v4, v4
	v_and_b32_e32 v3, 0xfffffe00, v3
	s_or_b64 s[14:15], vcc, s[0:1]
	v_cmp_eq_u32_e32 vcc, s86, v1
	v_cmp_eq_u32_e64 s[0:1], s22, v1
	v_max_f32_e32 v4, 0, v4
	v_lshlrev_b32_e32 v9, 1, v1
	v_cmp_lt_i32_e64 s[20:21], s86, v1
	v_or_b32_e32 v1, 0xc0, v157
	v_max_f32_e32 v5, v5, v5
	v_cndmask_b32_e64 v7, v3, v172, s[14:15]
	v_and_b32_e32 v4, 0xfffffe00, v4
	s_or_b64 s[18:19], vcc, s[0:1]
	v_cmp_eq_u32_e32 vcc, s86, v1
	v_cmp_eq_u32_e64 s[0:1], s22, v1
	v_max_f32_e32 v5, 0, v5
	v_xor_b32_e32 v3, 0x1ff, v8
	v_bitop3_b32 v7, v7, v8, s4 bitop3:0xf6
	v_cndmask_b32_e64 v8, v4, v172, s[18:19]
	v_and_b32_e32 v5, 0xfffffe00, v5
	s_or_b64 s[22:23], vcc, s[0:1]
	v_xor_b32_e32 v4, 0x1ff, v9
	v_bitop3_b32 v8, v8, v9, s4 bitop3:0xf6
	v_cndmask_b32_e64 v9, v5, v172, s[22:23]
	v_lshlrev_b32_e32 v10, 1, v1
	v_bitop3_b32 v9, v9, v10, s4 bitop3:0xf6
	v_cmp_lt_i32_e64 s[24:25], s86, v1
	s_mov_b32 s26, 0
	s_mov_b32 s32, -1
	v_cndmask_b32_e64 v7, v7, 0, s[16:17]
	v_cndmask_b32_e64 v8, v8, 0, s[20:21]
	v_xor_b32_e32 v5, 0x1ff, v10
	v_cndmask_b32_e64 v9, v9, 0, s[24:25]
	s_mov_b32 s27, 31
.LBB0_1527:
	s_lshl_b32 s0, 1, s27
	s_or_b32 s33, s0, s26
	v_cmp_le_u32_e32 vcc, s33, v6
	v_cmp_le_u32_e64 s[0:1], s33, v7
	v_cmp_le_u32_e64 s[28:29], s33, v8
	s_bcnt1_i32_b64 s34, vcc
	s_bcnt1_i32_b64 s0, s[0:1]
	v_cmp_le_u32_e64 s[30:31], s33, v9
	s_bcnt1_i32_b64 s1, s[28:29]
	s_add_i32 s0, s0, s34
	s_bcnt1_i32_b64 s28, s[30:31]
	s_add_i32 s0, s0, s1
	s_add_i32 s0, s0, s28
	s_cmp_gt_u32 s0, 15
	s_cselect_b32 s32, s0, s32
	s_cselect_b32 s26, s33, s26
	s_add_i32 s0, s27, -1
	s_lshl_b32 s0, 1, s0
	s_or_b32 s33, s0, s26
	v_cmp_le_u32_e32 vcc, s33, v6
	v_cmp_le_u32_e64 s[0:1], s33, v7
	v_cmp_le_u32_e64 s[28:29], s33, v8
	s_bcnt1_i32_b64 s34, vcc
	s_bcnt1_i32_b64 s0, s[0:1]
	v_cmp_le_u32_e64 s[30:31], s33, v9
	s_bcnt1_i32_b64 s1, s[28:29]
	s_add_i32 s0, s0, s34
	s_bcnt1_i32_b64 s28, s[30:31]
	s_add_i32 s0, s0, s1
	s_add_i32 s0, s0, s28
	s_cmp_gt_u32 s0, 15
	s_cselect_b32 s32, s0, s32
	s_cselect_b32 s26, s33, s26
	s_add_i32 s0, s27, -2
	s_lshl_b32 s0, 1, s0
	s_or_b32 s33, s0, s26
	v_cmp_le_u32_e32 vcc, s33, v6
	v_cmp_le_u32_e64 s[0:1], s33, v7
	v_cmp_le_u32_e64 s[28:29], s33, v8
	s_bcnt1_i32_b64 s34, vcc
	s_bcnt1_i32_b64 s0, s[0:1]
	v_cmp_le_u32_e64 s[30:31], s33, v9
	s_bcnt1_i32_b64 s1, s[28:29]
	s_add_i32 s0, s0, s34
	s_bcnt1_i32_b64 s28, s[30:31]
	s_add_i32 s0, s0, s1
	s_add_i32 s0, s0, s28
	s_cmp_gt_u32 s0, 15
	s_cselect_b32 s32, s0, s32
	s_cselect_b32 s26, s33, s26
	s_add_i32 s0, s27, -3
	s_lshl_b32 s1, 1, s0
	s_or_b32 s33, s1, s26
	v_sub_co_u32_e64 v1, s[34:35], s0, 1
	v_cmp_le_u32_e32 vcc, s33, v6
	v_cmp_le_u32_e64 s[0:1], s33, v7
	v_cmp_le_u32_e64 s[28:29], s33, v8
	s_bcnt1_i32_b64 s36, vcc
	s_bcnt1_i32_b64 s0, s[0:1]
	v_cmp_le_u32_e64 s[30:31], s33, v9
	s_bcnt1_i32_b64 s1, s[28:29]
	s_add_i32 s0, s0, s36
	s_bcnt1_i32_b64 s28, s[30:31]
	s_add_i32 s0, s0, s1
	s_add_i32 s0, s0, s28
	s_cmp_gt_u32 s0, 15
	s_cselect_b32 s32, s0, s32
	v_readfirstlane_b32 s27, v1
	s_cselect_b32 s26, s33, s26
	s_cmp_eq_u32 s32, 16
	s_cbranch_scc1 .Ltk_exit_1
	s_and_b64 vcc, exec, s[34:35]
	s_cbranch_vccz .LBB0_1527
.Ltk_exit_1:
	v_cmp_le_u32_e32 vcc, s26, v6
	s_xor_b64 s[34:35], s[12:13], -1
	v_lshl_or_b32 v1, v157, 2, v168
	v_lshlrev_b32_e64 v10, v156, 1
	s_and_b64 s[28:29], s[34:35], vcc
	s_and_saveexec_b64 s[0:1], s[28:29]
	ds_or_b32 v1, v10
	s_or_b64 exec, exec, s[0:1]
	v_cmp_le_u32_e32 vcc, s26, v7
	s_xor_b64 s[36:37], s[16:17], -1
	s_and_b64 s[28:29], s[36:37], vcc
	s_and_saveexec_b64 s[0:1], s[28:29]
	ds_or_b32 v1, v10 offset:256
	s_or_b64 exec, exec, s[0:1]
	v_cmp_le_u32_e32 vcc, s26, v8
	s_xor_b64 s[38:39], s[20:21], -1
	s_and_b64 s[28:29], s[38:39], vcc
	s_and_saveexec_b64 s[0:1], s[28:29]
	ds_or_b32 v1, v10 offset:512
	s_or_b64 exec, exec, s[0:1]
	v_cmp_le_u32_e32 vcc, s26, v9
	s_xor_b64 s[40:41], s[24:25], -1
	s_and_b64 s[26:27], s[40:41], vcc
	s_and_saveexec_b64 s[0:1], s[26:27]
	ds_or_b32 v1, v10 offset:768
	s_or_b64 exec, exec, s[0:1]
	v_add_u32_e32 v8, 16, v0
	ds_read2st64_b32 v[6:7], v8 offset0:132 offset1:133
	ds_read2st64_b32 v[10:11], v8 offset0:134 offset1:135
	s_mov_b32 s26, 0
	s_mov_b32 s32, -1
	s_mov_b32 s27, 31
	s_waitcnt lgkmcnt(1)
	v_max_f32_e32 v6, v6, v6
	v_max_f32_e32 v6, 0, v6
	v_and_b32_e32 v6, 0xfffffe00, v6
	v_max_f32_e32 v7, v7, v7
	v_cndmask_b32_e64 v6, v6, v172, s[10:11]
	v_max_f32_e32 v7, 0, v7
	v_or_b32_e32 v6, v6, v2
	v_cndmask_b32_e64 v9, v6, 0, s[12:13]
	v_and_b32_e32 v6, 0xfffffe00, v7
	v_cndmask_b32_e64 v6, v6, v172, s[14:15]
	v_or_b32_e32 v6, v6, v3
	v_cndmask_b32_e64 v8, v6, 0, s[16:17]
	s_waitcnt lgkmcnt(0)
	v_max_f32_e32 v6, v10, v10
	v_max_f32_e32 v6, 0, v6
	v_and_b32_e32 v6, 0xfffffe00, v6
	v_cndmask_b32_e64 v6, v6, v172, s[18:19]
	v_or_b32_e32 v6, v6, v4
	v_cndmask_b32_e64 v7, v6, 0, s[20:21]
	v_max_f32_e32 v6, v11, v11
	v_max_f32_e32 v6, 0, v6
	v_and_b32_e32 v6, 0xfffffe00, v6
	v_cndmask_b32_e64 v6, v6, v172, s[22:23]
	v_or_b32_e32 v6, v6, v5
	v_cndmask_b32_e64 v6, v6, 0, s[24:25]
.LBB0_1537:
	s_lshl_b32 s0, 1, s27
	s_or_b32 s33, s0, s26
	v_cmp_le_u32_e32 vcc, s33, v9
	v_cmp_le_u32_e64 s[0:1], s33, v8
	v_cmp_le_u32_e64 s[28:29], s33, v7
	s_bcnt1_i32_b64 s42, vcc
	s_bcnt1_i32_b64 s0, s[0:1]
	v_cmp_le_u32_e64 s[30:31], s33, v6
	s_bcnt1_i32_b64 s1, s[28:29]
	s_add_i32 s0, s0, s42
	s_bcnt1_i32_b64 s28, s[30:31]
	s_add_i32 s0, s0, s1
	s_add_i32 s0, s0, s28
	s_cmp_gt_u32 s0, 15
	s_cselect_b32 s32, s0, s32
	s_cselect_b32 s26, s33, s26
	s_add_i32 s0, s27, -1
	s_lshl_b32 s0, 1, s0
	s_or_b32 s33, s0, s26
	v_cmp_le_u32_e32 vcc, s33, v9
	v_cmp_le_u32_e64 s[0:1], s33, v8
	v_cmp_le_u32_e64 s[28:29], s33, v7
	s_bcnt1_i32_b64 s42, vcc
	s_bcnt1_i32_b64 s0, s[0:1]
	v_cmp_le_u32_e64 s[30:31], s33, v6
	s_bcnt1_i32_b64 s1, s[28:29]
	s_add_i32 s0, s0, s42
	s_bcnt1_i32_b64 s28, s[30:31]
	s_add_i32 s0, s0, s1
	s_add_i32 s0, s0, s28
	s_cmp_gt_u32 s0, 15
	s_cselect_b32 s32, s0, s32
	s_cselect_b32 s26, s33, s26
	s_add_i32 s0, s27, -2
	s_lshl_b32 s0, 1, s0
	s_or_b32 s33, s0, s26
	v_cmp_le_u32_e32 vcc, s33, v9
	v_cmp_le_u32_e64 s[0:1], s33, v8
	v_cmp_le_u32_e64 s[28:29], s33, v7
	s_bcnt1_i32_b64 s42, vcc
	s_bcnt1_i32_b64 s0, s[0:1]
	v_cmp_le_u32_e64 s[30:31], s33, v6
	s_bcnt1_i32_b64 s1, s[28:29]
	s_add_i32 s0, s0, s42
	s_bcnt1_i32_b64 s28, s[30:31]
	s_add_i32 s0, s0, s1
	s_add_i32 s0, s0, s28
	s_cmp_gt_u32 s0, 15
	s_cselect_b32 s32, s0, s32
	s_cselect_b32 s26, s33, s26
	s_add_i32 s0, s27, -3
	s_lshl_b32 s1, 1, s0
	s_or_b32 s27, s1, s26
	v_sub_co_u32_e64 v10, s[42:43], s0, 1
	v_cmp_le_u32_e32 vcc, s27, v9
	v_cmp_le_u32_e64 s[0:1], s27, v8
	v_cmp_le_u32_e64 s[28:29], s27, v7
	s_bcnt1_i32_b64 s33, vcc
	s_bcnt1_i32_b64 s0, s[0:1]
	v_cmp_le_u32_e64 s[30:31], s27, v6
	s_bcnt1_i32_b64 s1, s[28:29]
	s_add_i32 s0, s0, s33
	s_bcnt1_i32_b64 s28, s[30:31]
	s_add_i32 s0, s0, s1
	s_add_i32 s0, s0, s28
	s_cmp_gt_u32 s0, 15
	s_cselect_b32 s32, s0, s32
	s_cselect_b32 s26, s27, s26
	s_cmp_eq_u32 s32, 16
	s_cbranch_scc1 .Ltk_exit_2
	s_andn2_b64 vcc, exec, s[42:43]
	v_readfirstlane_b32 s27, v10
	s_cbranch_vccnz .LBB0_1537
.Ltk_exit_2:
	v_cmp_le_u32_e32 vcc, s26, v9
	v_lshlrev_b32_e64 v10, v156, 2
	s_and_b64 s[28:29], s[34:35], vcc
	s_and_saveexec_b64 s[0:1], s[28:29]
	ds_or_b32 v1, v10
	s_or_b64 exec, exec, s[0:1]
	v_cmp_le_u32_e32 vcc, s26, v8
	s_and_b64 s[28:29], s[36:37], vcc
	s_and_saveexec_b64 s[0:1], s[28:29]
	ds_or_b32 v1, v10 offset:256
	s_or_b64 exec, exec, s[0:1]
	v_cmp_le_u32_e32 vcc, s26, v7
	s_and_b64 s[28:29], s[38:39], vcc
	s_and_saveexec_b64 s[0:1], s[28:29]
	ds_or_b32 v1, v10 offset:512
	s_or_b64 exec, exec, s[0:1]
	v_cmp_le_u32_e32 vcc, s26, v6
	s_and_b64 s[26:27], s[40:41], vcc
	s_and_saveexec_b64 s[0:1], s[26:27]
	ds_or_b32 v1, v10 offset:768
	s_or_b64 exec, exec, s[0:1]
	v_add_u32_e32 v8, 32, v0
	ds_read2st64_b32 v[6:7], v8 offset0:136 offset1:137
	ds_read2st64_b32 v[10:11], v8 offset0:138 offset1:139
	s_mov_b32 s26, 0
	s_mov_b32 s32, -1
	s_mov_b32 s27, 31
	s_waitcnt lgkmcnt(1)
	v_max_f32_e32 v6, v6, v6
	v_max_f32_e32 v6, 0, v6
	v_and_b32_e32 v6, 0xfffffe00, v6
	v_max_f32_e32 v7, v7, v7
	v_cndmask_b32_e64 v6, v6, v172, s[10:11]
	v_max_f32_e32 v7, 0, v7
	v_or_b32_e32 v6, v6, v2
	v_cndmask_b32_e64 v9, v6, 0, s[12:13]
	v_and_b32_e32 v6, 0xfffffe00, v7
	v_cndmask_b32_e64 v6, v6, v172, s[14:15]
	v_or_b32_e32 v6, v6, v3
	v_cndmask_b32_e64 v8, v6, 0, s[16:17]
	s_waitcnt lgkmcnt(0)
	v_max_f32_e32 v6, v10, v10
	v_max_f32_e32 v6, 0, v6
	v_and_b32_e32 v6, 0xfffffe00, v6
	v_cndmask_b32_e64 v6, v6, v172, s[18:19]
	v_or_b32_e32 v6, v6, v4
	v_cndmask_b32_e64 v7, v6, 0, s[20:21]
	v_max_f32_e32 v6, v11, v11
	v_max_f32_e32 v6, 0, v6
	v_and_b32_e32 v6, 0xfffffe00, v6
	v_cndmask_b32_e64 v6, v6, v172, s[22:23]
	v_or_b32_e32 v6, v6, v5
	v_cndmask_b32_e64 v6, v6, 0, s[24:25]

.Ltk_exit_3:
	v_cmp_le_u32_e32 vcc, s26, v9
	v_lshlrev_b32_e64 v10, v156, 4
	s_and_b64 s[28:29], s[34:35], vcc
	s_and_saveexec_b64 s[0:1], s[28:29]
	ds_or_b32 v1, v10
	s_or_b64 exec, exec, s[0:1]
	v_cmp_le_u32_e32 vcc, s26, v8
	s_and_b64 s[28:29], s[36:37], vcc
	s_and_saveexec_b64 s[0:1], s[28:29]
	ds_or_b32 v1, v10 offset:256
	s_or_b64 exec, exec, s[0:1]
	v_cmp_le_u32_e32 vcc, s26, v7
	s_and_b64 s[28:29], s[38:39], vcc
	s_and_saveexec_b64 s[0:1], s[28:29]
	ds_or_b32 v1, v10 offset:512
	s_or_b64 exec, exec, s[0:1]
	v_cmp_le_u32_e32 vcc, s26, v6
	s_and_b64 s[26:27], s[40:41], vcc
	s_and_saveexec_b64 s[0:1], s[26:27]
	ds_or_b32 v1, v10 offset:768
	s_or_b64 exec, exec, s[0:1]
	v_add_u32_e32 v8, 48, v0
	ds_read2st64_b32 v[6:7], v8 offset0:140 offset1:141
	ds_read2st64_b32 v[10:11], v8 offset0:142 offset1:143
	s_mov_b32 s26, 0
	s_mov_b32 s32, -1
	s_mov_b32 s27, 31
	s_waitcnt lgkmcnt(1)
	v_max_f32_e32 v6, v6, v6
	v_max_f32_e32 v6, 0, v6
	v_and_b32_e32 v6, 0xfffffe00, v6
	v_max_f32_e32 v7, v7, v7
	v_cndmask_b32_e64 v6, v6, v172, s[10:11]
	v_max_f32_e32 v7, 0, v7
	v_or_b32_e32 v6, v6, v2
	v_cndmask_b32_e64 v9, v6, 0, s[12:13]
	v_and_b32_e32 v6, 0xfffffe00, v7
	v_cndmask_b32_e64 v6, v6, v172, s[14:15]
	v_or_b32_e32 v6, v6, v3
	v_cndmask_b32_e64 v8, v6, 0, s[16:17]
	s_waitcnt lgkmcnt(0)
	v_max_f32_e32 v6, v10, v10
	v_max_f32_e32 v6, 0, v6
	v_and_b32_e32 v6, 0xfffffe00, v6
	v_cndmask_b32_e64 v6, v6, v172, s[18:19]
	v_or_b32_e32 v6, v6, v4
	v_cndmask_b32_e64 v7, v6, 0, s[20:21]
	v_max_f32_e32 v6, v11, v11
	v_max_f32_e32 v6, 0, v6
	v_and_b32_e32 v6, 0xfffffe00, v6
	v_cndmask_b32_e64 v6, v6, v172, s[22:23]
	v_or_b32_e32 v6, v6, v5
	v_cndmask_b32_e64 v6, v6, 0, s[24:25]

.Ltk_exit_4:
	v_cmp_le_u32_e32 vcc, s26, v9
	v_lshlrev_b32_e64 v10, v156, 8
	s_and_b64 s[28:29], s[34:35], vcc
	s_and_saveexec_b64 s[0:1], s[28:29]
	ds_or_b32 v1, v10
	s_or_b64 exec, exec, s[0:1]
	v_cmp_le_u32_e32 vcc, s26, v8
	s_and_b64 s[28:29], s[36:37], vcc
	s_and_saveexec_b64 s[0:1], s[28:29]
	ds_or_b32 v1, v10 offset:256
	s_or_b64 exec, exec, s[0:1]
	v_cmp_le_u32_e32 vcc, s26, v7
	s_and_b64 s[28:29], s[38:39], vcc
	s_and_saveexec_b64 s[0:1], s[28:29]
	ds_or_b32 v1, v10 offset:512
	s_or_b64 exec, exec, s[0:1]
	v_cmp_le_u32_e32 vcc, s26, v6
	s_and_b64 s[26:27], s[40:41], vcc
	s_and_saveexec_b64 s[0:1], s[26:27]
	ds_or_b32 v1, v10 offset:768
	s_or_b64 exec, exec, s[0:1]
	v_add_u32_e32 v8, 64, v0
	ds_read2st64_b32 v[6:7], v8 offset0:144 offset1:145
	ds_read2st64_b32 v[10:11], v8 offset0:146 offset1:147
	s_mov_b32 s26, 0
	s_mov_b32 s32, -1
	s_mov_b32 s27, 31
	s_waitcnt lgkmcnt(1)
	v_max_f32_e32 v6, v6, v6
	v_max_f32_e32 v6, 0, v6
	v_and_b32_e32 v6, 0xfffffe00, v6
	v_max_f32_e32 v7, v7, v7
	v_cndmask_b32_e64 v6, v6, v172, s[10:11]
	v_max_f32_e32 v7, 0, v7
	v_or_b32_e32 v6, v6, v2
	v_cndmask_b32_e64 v9, v6, 0, s[12:13]
	v_and_b32_e32 v6, 0xfffffe00, v7
	v_cndmask_b32_e64 v6, v6, v172, s[14:15]
	v_or_b32_e32 v6, v6, v3
	v_cndmask_b32_e64 v8, v6, 0, s[16:17]
	s_waitcnt lgkmcnt(0)
	v_max_f32_e32 v6, v10, v10
	v_max_f32_e32 v6, 0, v6
	v_and_b32_e32 v6, 0xfffffe00, v6
	v_cndmask_b32_e64 v6, v6, v172, s[18:19]
	v_or_b32_e32 v6, v6, v4
	v_cndmask_b32_e64 v7, v6, 0, s[20:21]
	v_max_f32_e32 v6, v11, v11
	v_max_f32_e32 v6, 0, v6
	v_and_b32_e32 v6, 0xfffffe00, v6
	v_cndmask_b32_e64 v6, v6, v172, s[22:23]
	v_or_b32_e32 v6, v6, v5
	v_cndmask_b32_e64 v6, v6, 0, s[24:25]

.Ltk_exit_5:
	v_cmp_le_u32_e32 vcc, s26, v9
	v_lshlrev_b32_e64 v10, v156, 16
	s_and_b64 s[28:29], s[34:35], vcc
	s_and_saveexec_b64 s[0:1], s[28:29]
	ds_or_b32 v1, v10
	s_or_b64 exec, exec, s[0:1]
	v_cmp_le_u32_e32 vcc, s26, v8
	s_and_b64 s[28:29], s[36:37], vcc
	s_and_saveexec_b64 s[0:1], s[28:29]
	ds_or_b32 v1, v10 offset:256
	s_or_b64 exec, exec, s[0:1]
	v_cmp_le_u32_e32 vcc, s26, v7
	s_and_b64 s[28:29], s[38:39], vcc
	s_and_saveexec_b64 s[0:1], s[28:29]
	ds_or_b32 v1, v10 offset:512
	s_or_b64 exec, exec, s[0:1]
	v_cmp_le_u32_e32 vcc, s26, v6
	s_and_b64 s[26:27], s[40:41], vcc
	s_and_saveexec_b64 s[0:1], s[26:27]
	ds_or_b32 v1, v10 offset:768
	s_or_b64 exec, exec, s[0:1]
	v_add_u32_e32 v8, 0x50, v0
	ds_read2st64_b32 v[6:7], v8 offset0:148 offset1:149
	ds_read2st64_b32 v[10:11], v8 offset0:150 offset1:151
	s_mov_b32 s26, 0
	s_mov_b32 s32, -1
	s_mov_b32 s27, 31
	s_waitcnt lgkmcnt(1)
	v_max_f32_e32 v6, v6, v6
	v_max_f32_e32 v6, 0, v6
	v_and_b32_e32 v6, 0xfffffe00, v6
	v_max_f32_e32 v7, v7, v7
	v_cndmask_b32_e64 v6, v6, v172, s[10:11]
	v_max_f32_e32 v7, 0, v7
	v_or_b32_e32 v6, v6, v2
	v_cndmask_b32_e64 v9, v6, 0, s[12:13]
	v_and_b32_e32 v6, 0xfffffe00, v7
	v_cndmask_b32_e64 v6, v6, v172, s[14:15]
	v_or_b32_e32 v6, v6, v3
	v_cndmask_b32_e64 v8, v6, 0, s[16:17]
	s_waitcnt lgkmcnt(0)
	v_max_f32_e32 v6, v10, v10
	v_max_f32_e32 v6, 0, v6
	v_and_b32_e32 v6, 0xfffffe00, v6
	v_cndmask_b32_e64 v6, v6, v172, s[18:19]
	v_or_b32_e32 v6, v6, v4
	v_cndmask_b32_e64 v7, v6, 0, s[20:21]
	v_max_f32_e32 v6, v11, v11
	v_max_f32_e32 v6, 0, v6
	v_and_b32_e32 v6, 0xfffffe00, v6
	v_cndmask_b32_e64 v6, v6, v172, s[22:23]
	v_or_b32_e32 v6, v6, v5
	v_cndmask_b32_e64 v6, v6, 0, s[24:25]

.Ltk_exit_6:
	v_cmp_le_u32_e32 vcc, s26, v9
	v_lshlrev_b32_e64 v10, v156, 32
	s_and_b64 s[28:29], s[34:35], vcc
	s_and_saveexec_b64 s[0:1], s[28:29]
	ds_or_b32 v1, v10
	s_or_b64 exec, exec, s[0:1]
	v_cmp_le_u32_e32 vcc, s26, v8
	s_and_b64 s[28:29], s[36:37], vcc
	s_and_saveexec_b64 s[0:1], s[28:29]
	ds_or_b32 v1, v10 offset:256
	s_or_b64 exec, exec, s[0:1]
	v_cmp_le_u32_e32 vcc, s26, v7
	s_and_b64 s[28:29], s[38:39], vcc
	s_and_saveexec_b64 s[0:1], s[28:29]
	ds_or_b32 v1, v10 offset:512
	s_or_b64 exec, exec, s[0:1]
	v_cmp_le_u32_e32 vcc, s26, v6
	s_and_b64 s[26:27], s[40:41], vcc
	s_and_saveexec_b64 s[0:1], s[26:27]
	ds_or_b32 v1, v10 offset:768
	s_or_b64 exec, exec, s[0:1]
	v_add_u32_e32 v8, 0x60, v0
	ds_read2st64_b32 v[6:7], v8 offset0:152 offset1:153
	ds_read2st64_b32 v[10:11], v8 offset0:154 offset1:155
	s_mov_b32 s26, 0
	s_mov_b32 s32, -1
	s_mov_b32 s27, 31
	s_waitcnt lgkmcnt(1)
	v_max_f32_e32 v6, v6, v6
	v_max_f32_e32 v6, 0, v6
	v_and_b32_e32 v6, 0xfffffe00, v6
	v_max_f32_e32 v7, v7, v7
	v_cndmask_b32_e64 v6, v6, v172, s[10:11]
	v_max_f32_e32 v7, 0, v7
	v_or_b32_e32 v6, v6, v2
	v_cndmask_b32_e64 v9, v6, 0, s[12:13]
	v_and_b32_e32 v6, 0xfffffe00, v7
	v_cndmask_b32_e64 v6, v6, v172, s[14:15]
	v_or_b32_e32 v6, v6, v3
	v_cndmask_b32_e64 v8, v6, 0, s[16:17]
	s_waitcnt lgkmcnt(0)
	v_max_f32_e32 v6, v10, v10
	v_max_f32_e32 v6, 0, v6
	v_and_b32_e32 v6, 0xfffffe00, v6
	v_cndmask_b32_e64 v6, v6, v172, s[18:19]
	v_or_b32_e32 v6, v6, v4
	v_cndmask_b32_e64 v7, v6, 0, s[20:21]
	v_max_f32_e32 v6, v11, v11
	v_max_f32_e32 v6, 0, v6
	v_and_b32_e32 v6, 0xfffffe00, v6
	v_cndmask_b32_e64 v6, v6, v172, s[22:23]
	v_or_b32_e32 v6, v6, v5
	v_cndmask_b32_e64 v6, v6, 0, s[24:25]

.Ltk_exit_7:
	v_cmp_le_u32_e32 vcc, s26, v9
	v_lshlrev_b32_e64 v10, v156, 64
	s_and_b64 s[28:29], s[34:35], vcc
	s_and_saveexec_b64 s[0:1], s[28:29]
	ds_or_b32 v1, v10
	s_or_b64 exec, exec, s[0:1]
	v_cmp_le_u32_e32 vcc, s26, v8
	s_and_b64 s[28:29], s[36:37], vcc
	s_and_saveexec_b64 s[0:1], s[28:29]
	ds_or_b32 v1, v10 offset:256
	s_or_b64 exec, exec, s[0:1]
	v_cmp_le_u32_e32 vcc, s26, v7
	s_and_b64 s[28:29], s[38:39], vcc
	s_and_saveexec_b64 s[0:1], s[28:29]
	ds_or_b32 v1, v10 offset:512
	s_or_b64 exec, exec, s[0:1]
	v_cmp_le_u32_e32 vcc, s26, v6
	s_and_b64 s[26:27], s[40:41], vcc
	s_and_saveexec_b64 s[0:1], s[26:27]
	ds_or_b32 v1, v10 offset:768
	s_or_b64 exec, exec, s[0:1]
	v_add_u32_e32 v0, 0x70, v0
	ds_read2st64_b32 v[6:7], v0 offset0:156 offset1:157
	ds_read2st64_b32 v[8:9], v0 offset0:158 offset1:159
	s_mov_b32 s26, 0
	s_mov_b32 s32, -1
	s_waitcnt lgkmcnt(1)
	v_max_f32_e32 v0, v6, v6
	v_max_f32_e32 v0, 0, v0
	v_and_b32_e32 v0, 0xfffffe00, v0
	v_max_f32_e32 v6, v7, v7
	v_cndmask_b32_e64 v0, v0, v172, s[10:11]
	v_max_f32_e32 v7, 0, v6
	v_or_b32_e32 v0, v0, v2
	v_cndmask_b32_e64 v6, v0, 0, s[12:13]
	v_and_b32_e32 v0, 0xfffffe00, v7
	v_cndmask_b32_e64 v0, v0, v172, s[14:15]
	v_or_b32_e32 v0, v0, v3
	v_cndmask_b32_e64 v3, v0, 0, s[16:17]
	s_waitcnt lgkmcnt(0)
	v_max_f32_e32 v0, v8, v8
	v_max_f32_e32 v0, 0, v0
	v_and_b32_e32 v0, 0xfffffe00, v0
	v_cndmask_b32_e64 v0, v0, v172, s[18:19]
	v_or_b32_e32 v0, v0, v4
	v_cndmask_b32_e64 v2, v0, 0, s[20:21]
	v_max_f32_e32 v0, v9, v9
	v_max_f32_e32 v0, 0, v0
	v_and_b32_e32 v0, 0xfffffe00, v0
	v_cndmask_b32_e64 v0, v0, v172, s[22:23]
	v_or_b32_e32 v0, v0, v5
	v_cndmask_b32_e64 v0, v0, 0, s[24:25]
	s_mov_b32 s14, 31
.LBB0_1597:
	s_lshl_b32 s0, 1, s14
	s_or_b32 s15, s0, s26
	v_cmp_le_u32_e32 vcc, s15, v6
	v_cmp_le_u32_e64 s[0:1], s15, v3
	v_cmp_le_u32_e64 s[10:11], s15, v2
	s_bcnt1_i32_b64 s16, vcc
	s_bcnt1_i32_b64 s0, s[0:1]
	v_cmp_le_u32_e64 s[12:13], s15, v0
	s_bcnt1_i32_b64 s1, s[10:11]
	s_add_i32 s0, s0, s16
	s_bcnt1_i32_b64 s10, s[12:13]
	s_add_i32 s0, s0, s1
	s_add_i32 s0, s0, s10
	s_cmp_gt_u32 s0, 15
	s_cselect_b32 s32, s0, s32
	s_cselect_b32 s15, s15, s26
	s_add_i32 s0, s14, -1
	s_lshl_b32 s0, 1, s0
	s_or_b32 s16, s0, s15
	v_cmp_le_u32_e32 vcc, s16, v6
	v_cmp_le_u32_e64 s[0:1], s16, v3
	v_cmp_le_u32_e64 s[10:11], s16, v2
	s_bcnt1_i32_b64 s17, vcc
	s_bcnt1_i32_b64 s0, s[0:1]
	v_cmp_le_u32_e64 s[12:13], s16, v0
	s_bcnt1_i32_b64 s1, s[10:11]
	s_add_i32 s0, s0, s17
	s_bcnt1_i32_b64 s10, s[12:13]
	s_add_i32 s0, s0, s1
	s_add_i32 s0, s0, s10
	s_cmp_gt_u32 s0, 15
	s_cselect_b32 s32, s0, s32
	s_cselect_b32 s15, s16, s15
	s_add_i32 s0, s14, -2
	s_lshl_b32 s0, 1, s0
	s_or_b32 s16, s0, s15
	v_cmp_le_u32_e32 vcc, s16, v6
	v_cmp_le_u32_e64 s[0:1], s16, v3
	v_cmp_le_u32_e64 s[10:11], s16, v2
	s_bcnt1_i32_b64 s17, vcc
	s_bcnt1_i32_b64 s0, s[0:1]
	v_cmp_le_u32_e64 s[12:13], s16, v0
	s_bcnt1_i32_b64 s1, s[10:11]
	s_add_i32 s0, s0, s17
	s_bcnt1_i32_b64 s10, s[12:13]
	s_add_i32 s0, s0, s1
	s_add_i32 s0, s0, s10
	s_cmp_gt_u32 s0, 15
	s_cselect_b32 s32, s0, s32
	s_cselect_b32 s16, s16, s15
	s_add_i32 s0, s14, -3
	s_lshl_b32 s1, 1, s0
	s_or_b32 s17, s1, s16
	v_sub_co_u32_e64 v4, s[14:15], s0, 1
	v_cmp_le_u32_e32 vcc, s17, v6
	v_cmp_le_u32_e64 s[0:1], s17, v3
	v_cmp_le_u32_e64 s[10:11], s17, v2
	s_bcnt1_i32_b64 s18, vcc
	s_bcnt1_i32_b64 s0, s[0:1]
	v_cmp_le_u32_e64 s[12:13], s17, v0
	s_bcnt1_i32_b64 s1, s[10:11]
	s_add_i32 s0, s0, s18
	s_bcnt1_i32_b64 s10, s[12:13]
	s_add_i32 s0, s0, s1
	s_add_i32 s0, s0, s10
	s_cmp_gt_u32 s0, 15
	s_cselect_b32 s32, s0, s32
	s_cselect_b32 s26, s17, s16
	s_cmp_eq_u32 s32, 16
	s_cbranch_scc1 .Ltk_exit_8
	s_andn2_b64 vcc, exec, s[14:15]
	v_readfirstlane_b32 s14, v4
	s_cbranch_vccnz .LBB0_1597
.Ltk_exit_8:
	s_movk_i32 s0, 0x80
	v_cmp_le_u32_e32 vcc, s26, v6
	v_lshlrev_b32_e64 v4, v156, s0
	s_and_b64 s[10:11], s[34:35], vcc
	s_and_saveexec_b64 s[0:1], s[10:11]
	ds_or_b32 v1, v4
	s_or_b64 exec, exec, s[0:1]
	v_cmp_le_u32_e32 vcc, s26, v3
	s_and_b64 s[10:11], s[36:37], vcc
	s_and_saveexec_b64 s[0:1], s[10:11]
	ds_or_b32 v1, v4 offset:256
	s_or_b64 exec, exec, s[0:1]
	v_cmp_le_u32_e32 vcc, s26, v2
	s_and_b64 s[10:11], s[38:39], vcc
	s_and_saveexec_b64 s[0:1], s[10:11]
	ds_or_b32 v1, v4 offset:512
	s_or_b64 exec, exec, s[0:1]
	v_cmp_le_u32_e32 vcc, s26, v0
	s_and_b64 s[10:11], s[40:41], vcc
	s_and_saveexec_b64 s[0:1], s[10:11]
	ds_or_b32 v1, v4 offset:768
	s_or_b64 exec, exec, s[0:1]
	v_mov_b32_e32 v3, v220
	s_waitcnt lgkmcnt(0)
	s_barrier
	s_nop 0
	v_and_b32_e32 v4, 63, v3
	v_lshlrev_b32_e32 v0, 2, v4
	v_or_b32_e32 v1, 0x10200, v0
	v_or_b32_e32 v2, 0x10300, v0
	v_or_b32_e32 v5, 0x10400, v0
	v_or_b32_e32 v0, 0x10500, v0
	ds_read_b32 v1, v1
	ds_read_b32 v2, v2
	ds_read_b32 v5, v5
	ds_read_b32 v0, v0
	s_waitcnt lgkmcnt(3)
	v_cmp_ne_u32_e64 s[10:11], 0, v1
	s_waitcnt lgkmcnt(2)
	v_cmp_ne_u32_e64 s[12:13], 0, v2
	s_waitcnt lgkmcnt(1)
	v_cmp_ne_u32_e64 s[14:15], 0, v5
	s_waitcnt lgkmcnt(0)
	v_cmp_ne_u32_e64 s[16:17], 0, v0
	s_mov_b64 vcc, s[10:11]
	s_cbranch_vccz .LBB0_1609
	s_ff1_i32_b64 s94, s[10:11]
	s_cbranch_execz .LBB0_1610
	s_branch .LBB0_1616
